# attention band steps (first step of the band loop body): causal mask + row-max tree + rescale decision moved from the serial section into the first nine P.V gaps
# baseline (speedup 1.0000x reference)
.LBB0_332:
	v_lshl_add_u64 v[218:219], v[214:215], 0, s[36:37]
	s_mov_b64 s[4:5], 0x4c020000
	s_lshl_b32 s70, s67, 1
	v_lshl_add_u64 v[92:93], v[218:219], 0, s[4:5]
	s_add_i32 s14, s70, s64
	s_mov_b32 s4, m0
	s_mov_b32 m0, s14
	s_nop 0
	global_load_lds_dwordx4 v[92:93], off
	s_mov_b32 m0, s4
	s_mov_b64 s[4:5], 0x4c020080
	v_lshl_add_u64 v[92:93], v[218:219], 0, s[4:5]
	s_add_i32 s4, s14, 0x2000
	s_mov_b32 s5, m0
	s_mov_b32 m0, s4
	s_nop 0
	global_load_lds_dwordx4 v[92:93], off
	s_mov_b32 m0, s5
	s_add_i32 s25, s69, s24
	s_waitcnt lgkmcnt(14)
	v_mfma_f32_32x32x16_bf16 v[32:47], v[164:167], v[208:211], v[32:47]
	v_add_u32_e32 v229, 0xffffffa5, v222
	v_add_u32_e32 v228, 0xffffff85, v222
	v_cmp_le_i32_e32 vcc, v229, v245
	s_nop 1
	v_cndmask_b32_e32 v112, v233, v112, vcc
	v_cmp_lt_i32_e32 vcc, v228, v245
	s_nop 1
	v_cndmask_b32_e32 v129, v233, v129, vcc
	v_cmp_le_i32_e32 vcc, v228, v245
	v_add_u32_e32 v228, 0xffffffa6, v222
	s_nop 0
	v_cndmask_b32_e32 v128, v233, v128, vcc
	v_cmp_le_i32_e32 vcc, v228, v245
	v_add_u32_e32 v228, 0xffffff87, v222
	s_nop 0
	v_cndmask_b32_e32 v113, v233, v113, vcc
	v_cmp_le_i32_e32 vcc, v228, v245
	v_add_u32_e32 v228, 0xffffffa7, v222
	s_nop 0
	ds_read_b64_tr_b16 v[92:93], v212 offset:32768
	ds_read_b64_tr_b16 v[94:95], v212 offset:33280
	s_waitcnt lgkmcnt(14)
	v_mfma_f32_32x32x16_bf16 v[48:63], v[164:167], v[96:99], v[48:63]
	v_cndmask_b32_e32 v130, v233, v130, vcc
	v_cmp_le_i32_e32 vcc, v228, v245
	v_add_u32_e32 v228, 0xffffff88, v222
	s_nop 0
	v_cndmask_b32_e32 v114, v233, v114, vcc
	v_cmp_le_i32_e32 vcc, v228, v245
	v_add_u32_e32 v228, 0xffffffa8, v222
	s_nop 0
	v_cndmask_b32_e32 v131, v233, v131, vcc
	v_cmp_le_i32_e32 vcc, v228, v245
	v_add_u32_e32 v228, 0xffffff8d, v222
	s_nop 0
	v_cndmask_b32_e32 v115, v233, v115, vcc
	v_cmp_le_i32_e32 vcc, v228, v245
	v_add_u32_e32 v228, 0xffffffad, v222
	s_nop 0
	v_cndmask_b32_e32 v132, v233, v132, vcc
	v_cmp_le_i32_e32 vcc, v228, v245
	v_add_u32_e32 v228, 0xffffff8e, v222
	ds_read_b64_tr_b16 v[96:97], v212 offset:36864
	ds_read_b64_tr_b16 v[98:99], v212 offset:37376
	s_waitcnt lgkmcnt(14)
	v_mfma_f32_32x32x16_bf16 v[32:47], v[156:159], v[100:103], v[32:47]
	s_nop 0
	v_cndmask_b32_e32 v116, v233, v116, vcc
	v_cmp_le_i32_e32 vcc, v228, v245
	v_add_u32_e32 v228, 0xffffffae, v222
	s_nop 0
	v_cndmask_b32_e32 v133, v233, v133, vcc
	v_cmp_le_i32_e32 vcc, v228, v245
	v_add_u32_e32 v228, 0xffffff8f, v222
	s_nop 0
	v_cndmask_b32_e32 v117, v233, v117, vcc
	v_cmp_le_i32_e32 vcc, v228, v245
	v_add_u32_e32 v228, 0xffffffaf, v222
	s_nop 0
	v_cndmask_b32_e32 v134, v233, v134, vcc
	v_cmp_le_i32_e32 vcc, v228, v245
	v_add_u32_e32 v228, 0xffffff90, v222
	s_nop 0
	v_cndmask_b32_e32 v118, v233, v118, vcc
	v_cmp_le_i32_e32 vcc, v228, v245
	ds_read_b64_tr_b16 v[100:101], v212 offset:33792
	ds_read_b64_tr_b16 v[102:103], v212 offset:34304
	s_waitcnt lgkmcnt(14)
	v_mfma_f32_32x32x16_bf16 v[48:63], v[156:159], v[104:107], v[48:63]
	v_add_u32_e32 v228, 0xffffffb0, v222
	s_nop 0
	v_cndmask_b32_e32 v135, v233, v135, vcc
	v_cmp_le_i32_e32 vcc, v228, v245
	v_add_u32_e32 v228, 0xffffff95, v222
	s_nop 0
	v_cndmask_b32_e32 v119, v233, v119, vcc
	v_cmp_le_i32_e32 vcc, v228, v245
	v_add_u32_e32 v228, 0xffffffb5, v222
	s_nop 0
	v_cndmask_b32_e32 v136, v233, v136, vcc
	v_cmp_le_i32_e32 vcc, v228, v245
	v_add_u32_e32 v228, 0xffffff96, v222
	s_nop 0
	v_cndmask_b32_e32 v120, v233, v120, vcc
	v_cmp_le_i32_e32 vcc, v228, v245
	v_add_u32_e32 v228, 0xffffffb6, v222
	s_nop 0
	v_cndmask_b32_e32 v137, v233, v137, vcc
	ds_read_b64_tr_b16 v[104:105], v212 offset:37888
	ds_read_b64_tr_b16 v[106:107], v212 offset:38400
	s_waitcnt lgkmcnt(14)
	v_mfma_f32_32x32x16_bf16 v[32:47], v[148:151], v[108:111], v[32:47]
	v_cmp_le_i32_e32 vcc, v228, v245
	v_add_u32_e32 v228, 0xffffff97, v222
	s_nop 0
	v_cndmask_b32_e32 v121, v233, v121, vcc
	v_cmp_le_i32_e32 vcc, v228, v245
	v_add_u32_e32 v228, 0xffffffb7, v222
	s_nop 0
	v_cndmask_b32_e32 v138, v233, v138, vcc
	v_cmp_le_i32_e32 vcc, v228, v245
	v_add_u32_e32 v228, 0xffffff98, v222
	s_nop 0
	v_cndmask_b32_e32 v122, v233, v122, vcc
	v_cmp_le_i32_e32 vcc, v228, v245
	v_add_u32_e32 v228, 0xffffffb8, v222
	s_nop 0
	v_cndmask_b32_e32 v139, v233, v139, vcc
	v_cmp_le_i32_e32 vcc, v228, v245
	v_add_u32_e32 v228, 0xffffff9d, v222
	s_nop 0
	ds_read_b64_tr_b16 v[108:109], v212 offset:34816
	ds_read_b64_tr_b16 v[110:111], v212 offset:35328
	s_waitcnt lgkmcnt(14)
	v_mfma_f32_32x32x16_bf16 v[48:63], v[148:151], v[80:83], v[48:63]
	v_cndmask_b32_e32 v123, v233, v123, vcc
	v_cmp_le_i32_e32 vcc, v228, v245
	v_add_u32_e32 v228, 0xffffffbd, v222
	s_nop 0
	v_cndmask_b32_e32 v140, v233, v140, vcc
	v_cmp_le_i32_e32 vcc, v228, v245
	v_add_u32_e32 v228, 0xffffff9e, v222
	s_nop 0
	v_cndmask_b32_e32 v124, v233, v124, vcc
	v_cmp_le_i32_e32 vcc, v228, v245
	v_add_u32_e32 v228, 0xffffffbe, v222
	s_nop 0
	v_cndmask_b32_e32 v141, v233, v141, vcc
	v_cmp_le_i32_e32 vcc, v228, v245
	v_add_u32_e32 v228, 0xffffff9f, v222
	s_nop 0
	v_cndmask_b32_e32 v125, v233, v125, vcc
	v_cmp_le_i32_e32 vcc, v228, v245
	v_add_u32_e32 v228, 0xffffffbf, v222
	ds_read_b64_tr_b16 v[80:81], v212 offset:38912
	ds_read_b64_tr_b16 v[82:83], v212 offset:39424
	s_waitcnt lgkmcnt(14)
	v_mfma_f32_32x32x16_bf16 v[32:47], v[144:147], v[84:87], v[32:47]
	s_nop 0
	v_cndmask_b32_e32 v142, v233, v142, vcc
	v_cmp_le_i32_e32 vcc, v228, v245
	v_add_u32_e32 v228, 0xffffffa0, v222
	s_nop 0
	v_cndmask_b32_e32 v126, v233, v126, vcc
	v_cmp_le_i32_e32 vcc, v228, v245
	v_subrev_u32_e32 v228, 64, v222
	s_nop 0
	v_cndmask_b32_e32 v143, v233, v143, vcc
	v_cmp_le_i32_e32 vcc, v228, v245
	s_nop 1
	v_cndmask_b32_e32 v127, v233, v127, vcc
	v_max_f32_e32 v228, v129, v129
	v_max_f32_e32 v229, v128, v128
	v_max_f32_e32 v228, v229, v228
	v_max3_f32 v229, v130, v131, v113
	v_max3_f32 v228, v228, v112, v114
	v_max3_f32 v228, v228, v115, v132
	ds_read_b64_tr_b16 v[84:85], v212 offset:35840
	ds_read_b64_tr_b16 v[86:87], v212 offset:36352
	s_waitcnt lgkmcnt(14)
	v_mfma_f32_32x32x16_bf16 v[48:63], v[144:147], v[88:91], v[48:63]
	v_max3_f32 v229, v229, v134, v135
	v_max3_f32 v228, v228, v133, v116
	v_max3_f32 v229, v229, v118, v119
	v_max3_f32 v228, v228, v117, v136
	v_max3_f32 v229, v229, v138, v139
	v_max3_f32 v228, v228, v137, v120
	v_max3_f32 v229, v229, v122, v123
	v_max3_f32 v228, v228, v121, v140
	v_max3_f32 v229, v229, v142, v143
	v_max3_f32 v228, v228, v141, v124
	v_max3_f32 v229, v229, v126, v127
	v_max3_f32 v228, v228, v125, v229
	v_mov_b32_e32 v229, v228
	s_nop 1
	v_permlane32_swap_b32_e32 v228, v229
	v_max_f32_e32 v229, v229, v229
	v_max_f32_e32 v228, v228, v228
	v_max_f32_e32 v228, v228, v229
	ds_read_b64_tr_b16 v[88:89], v212 offset:39936
	ds_read_b64_tr_b16 v[90:91], v212 offset:40448
	s_waitcnt lgkmcnt(14)
	v_mfma_f32_32x32x16_bf16 v[16:31], v[164:167], v[92:95], v[16:31]
	v_cmp_lt_f32_e32 vcc, s33, v228
	s_cmp_lg_u64 vcc, 0
	v_add_f32_e32 v223, v249, v176
	s_cselect_b64 s[4:5], -1, 0
	s_cbranch_vccnz .LBB0_372
.LBB0_335:
	v_exp_f32_e32 v128, v128
	v_exp_f32_e32 v129, v129
	v_add_u32_e32 v92, s67, v247
	ds_read_b128 v[204:207], v92
	ds_read_b128 v[200:203], v92 offset:512
	s_waitcnt lgkmcnt(14)
	v_mfma_f32_32x32x16_bf16 v[0:15], v[164:167], v[96:99], v[0:15]
	v_exp_f32_e32 v130, v130
	v_exp_f32_e32 v131, v131
	v_exp_f32_e32 v132, v132
	v_exp_f32_e32 v133, v133
	v_exp_f32_e32 v134, v134
	ds_read_b128 v[196:199], v92 offset:2048
	ds_read_b128 v[192:195], v92 offset:2560
	s_waitcnt lgkmcnt(14)
	v_mfma_f32_32x32x16_bf16 v[16:31], v[156:159], v[100:103], v[16:31]
	v_exp_f32_e32 v135, v135
	v_exp_f32_e32 v136, v136
	v_exp_f32_e32 v137, v137
	v_exp_f32_e32 v138, v138
	v_exp_f32_e32 v139, v139
	ds_read_b128 v[188:191], v92 offset:4096
	ds_read_b128 v[184:187], v92 offset:4608
	s_waitcnt lgkmcnt(14)
	v_mfma_f32_32x32x16_bf16 v[0:15], v[156:159], v[104:107], v[0:15]
	v_exp_f32_e32 v140, v140
	v_exp_f32_e32 v141, v141
	v_exp_f32_e32 v142, v142
	v_exp_f32_e32 v143, v143
	v_exp_f32_e32 v112, v112
	ds_read_b128 v[180:183], v92 offset:6144
	ds_read_b128 v[176:179], v92 offset:6656
	s_waitcnt lgkmcnt(14)
	v_mfma_f32_32x32x16_bf16 v[16:31], v[148:151], v[108:111], v[16:31]
	v_exp_f32_e32 v113, v113
	v_exp_f32_e32 v114, v114
	v_exp_f32_e32 v115, v115
	v_exp_f32_e32 v116, v116
	v_exp_f32_e32 v117, v117
	s_waitcnt lgkmcnt(12)
	v_mfma_f32_32x32x16_bf16 v[0:15], v[148:151], v[80:83], v[0:15]
	v_exp_f32_e32 v118, v118
	v_exp_f32_e32 v119, v119
	v_exp_f32_e32 v120, v120
	v_exp_f32_e32 v121, v121
	v_exp_f32_e32 v122, v122
	s_waitcnt lgkmcnt(10)
	v_mfma_f32_32x32x16_bf16 v[16:31], v[144:147], v[84:87], v[16:31]
	v_exp_f32_e32 v123, v123
	v_exp_f32_e32 v124, v124
	v_exp_f32_e32 v125, v125
	v_exp_f32_e32 v126, v126
	v_exp_f32_e32 v127, v127
	s_waitcnt lgkmcnt(8)
	v_mfma_f32_32x32x16_bf16 v[0:15], v[144:147], v[88:91], v[0:15]
	s_mov_b64 s[14:15], -1
	s_and_b64 vcc, exec, s[30:31]
	s_cbranch_vccnz .LBB0_360
	s_andn2_b64 vcc, exec, s[14:15]
	s_cbranch_vccz .LBB0_365

.LBB0_372:
	v_max_f32_e32 v64, v228, v228
	v_max_f32_e32 v228, 0, v64
	v_exp_f32_e64 v229, -v228
	v_add_f32_e32 v246, v246, v228
	v_xor_b32_e32 v64, 0x80000000, v246
	v_mov_b32_e32 v65, v64
	v_mov_b32_e32 v66, v64
	v_mov_b32_e32 v67, v64
	v_mov_b32_e32 v68, v64
	v_mov_b32_e32 v69, v64
	v_mov_b32_e32 v70, v64
	v_mov_b32_e32 v71, v64
	v_mov_b32_e32 v72, v64
	v_mov_b32_e32 v73, v64
	v_mov_b32_e32 v74, v64
	v_mov_b32_e32 v75, v64
	v_mov_b32_e32 v76, v64
	v_mov_b32_e32 v77, v64
	v_mov_b32_e32 v78, v64
	v_mov_b32_e32 v79, v64
	s_and_saveexec_b64 s[14:15], s[2:3]
	ds_write_b32 v243, v229
	s_or_b64 exec, exec, s[14:15]
	v_sub_f32_e32 v143, v143, v228
	v_sub_f32_e32 v142, v142, v228
	v_sub_f32_e32 v141, v141, v228
	v_sub_f32_e32 v140, v140, v228
	v_sub_f32_e32 v139, v139, v228
	v_sub_f32_e32 v138, v138, v228
	v_sub_f32_e32 v137, v137, v228
	v_sub_f32_e32 v136, v136, v228
	v_sub_f32_e32 v135, v135, v228
	v_sub_f32_e32 v134, v134, v228
	v_sub_f32_e32 v133, v133, v228
	v_sub_f32_e32 v132, v132, v228
	v_sub_f32_e32 v131, v131, v228
	v_sub_f32_e32 v130, v130, v228
	v_sub_f32_e32 v129, v129, v228
	v_sub_f32_e32 v128, v128, v228
	v_sub_f32_e32 v127, v127, v228
	v_sub_f32_e32 v126, v126, v228
	v_sub_f32_e32 v125, v125, v228
	v_sub_f32_e32 v124, v124, v228
	v_sub_f32_e32 v123, v123, v228
	v_sub_f32_e32 v122, v122, v228
	v_sub_f32_e32 v121, v121, v228
	v_sub_f32_e32 v120, v120, v228
	v_sub_f32_e32 v119, v119, v228
	v_sub_f32_e32 v118, v118, v228
	v_sub_f32_e32 v117, v117, v228
	v_sub_f32_e32 v116, v116, v228
	v_sub_f32_e32 v115, v115, v228
	v_sub_f32_e32 v114, v114, v228
	v_sub_f32_e32 v113, v113, v228
	v_sub_f32_e32 v112, v112, v228
	v_mul_f32_e32 v223, v223, v229
	s_waitcnt lgkmcnt(0)
	s_branch .LBB0_335
